# convert phase: norm-gain loads hoisted ahead of the next-tile prefetch as 4x dwordx4 with a counted vmcnt(4) (prefetch loads always issued under exec mask), instead of 8 serialized load+vmcnt(0)
# speedup vs baseline: 1.0322x; 1.0036x over previous
.LBB0_81:
	s_lshr_b32 s18, s39, 6
	s_abs_i32 s19, s18
	s_waitcnt vmcnt(0)
	s_and_b64 vcc, exec, s[0:1]
	s_cbranch_vccnz .Lcv_nogain
	s_cmp_eq_u64 s[6:7], 0
	s_cbranch_scc1 .Lcv_nogain
	v_add_u32_e32 v78, s8, v16
	v_lshlrev_b32_e32 v78, 2, v78
	global_load_dwordx4 v[60:63], v78, s[6:7]
	global_load_dwordx4 v[64:67], v78, s[6:7] offset:16
	global_load_dwordx4 v[68:71], v78, s[6:7] offset:32
	global_load_dwordx4 v[72:75], v78, s[6:7] offset:48
.Lcv_nogain:
	v_cvt_f32_u32_e32 v0, s19
	s_sub_i32 s23, 0, s19
	s_abs_i32 s20, s9
	s_xor_b32 s22, s9, s18
	v_rcp_iflag_f32_e32 v0, v0
	s_ashr_i32 s22, s22, 31
	v_mov_b32_e32 v4, 0
	v_mov_b32_e32 v5, 0
	v_mul_f32_e32 v0, 0x4f7ffffe, v0
	v_cvt_u32_f32_e32 v0, v0
	v_mov_b32_e32 v6, 0
	v_mov_b32_e32 v7, 0
	v_readfirstlane_b32 s37, v0
	s_mul_i32 s23, s23, s37
	s_mul_hi_u32 s23, s37, s23
	s_add_i32 s37, s37, s23
	s_mul_hi_u32 s23, s20, s37
	s_mul_i32 s37, s23, s19
	s_sub_i32 s20, s20, s37
	s_add_i32 s38, s23, 1
	s_sub_i32 s37, s20, s19
	s_cmp_ge_u32 s20, s19
	s_cselect_b32 s23, s38, s23
	s_cselect_b32 s20, s37, s20
	s_add_i32 s37, s23, 1
	s_cmp_ge_u32 s20, s19
	s_cselect_b32 s19, s37, s23
	s_xor_b32 s19, s19, s22
	s_sub_i32 s19, s19, s22
	s_lshl_b32 s20, s19, 6
	s_mul_i32 s19, s19, s18
	s_sub_i32 s9, s9, s19
	s_lshl_b32 s22, s9, 6
	v_or_b32_e32 v0, s22, v39
	v_cmp_gt_i32_e32 vcc, s21, v0
	v_ashrrev_i32_e32 v1, 31, v0
	v_add_u32_e32 v22, s20, v40
	s_and_b64 s[18:19], s[2:3], vcc
	v_lshl_add_u64 v[20:21], v[0:1], 2, s[16:17]
	v_mov_b32_e32 v0, 0
	s_and_saveexec_b64 s[16:17], s[18:19]
	v_mad_u64_u32 v[2:3], s[38:39], v22, s21, 0
	v_ashrrev_i32_e32 v1, 31, v22
	v_mov_b32_e32 v4, v3
	v_mad_u64_u32 v[4:5], s[38:39], v1, s21, v[4:5]
	v_mov_b32_e32 v3, v4
	v_lshl_add_u64 v[2:3], v[2:3], 2, v[20:21]
	global_load_dwordx4 v[4:7], v[2:3], off
.LBB0_83:
	s_or_b64 exec, exec, s[16:17]
	v_mov_b32_e32 v1, 0
	v_mov_b32_e32 v2, 0
	v_mov_b32_e32 v3, 0
	s_and_saveexec_b64 s[16:17], s[18:19]
	v_add_u32_e32 v0, 16, v22
	v_ashrrev_i32_e32 v3, 31, v0
	v_mad_u64_u32 v[0:1], s[38:39], v0, s21, 0
	v_mov_b32_e32 v2, v1
	v_mad_u64_u32 v[2:3], s[38:39], v3, s21, v[2:3]
	v_mov_b32_e32 v1, v2
	v_lshl_add_u64 v[0:1], v[0:1], 2, v[20:21]
	global_load_dwordx4 v[0:3], v[0:1], off
.LBB0_85:
	s_or_b64 exec, exec, s[16:17]
	v_mov_b32_e32 v8, 0
	v_mov_b32_e32 v12, 0
	v_mov_b32_e32 v13, 0
	v_mov_b32_e32 v14, 0
	v_mov_b32_e32 v15, 0
	s_and_saveexec_b64 s[16:17], s[18:19]
	v_add_u32_e32 v9, 32, v22
	v_mad_u64_u32 v[10:11], s[38:39], v9, s21, 0
	v_ashrrev_i32_e32 v13, 31, v9
	v_mov_b32_e32 v12, v11
	v_mad_u64_u32 v[12:13], s[38:39], v13, s21, v[12:13]
	v_mov_b32_e32 v11, v12
	v_lshl_add_u64 v[10:11], v[10:11], 2, v[20:21]
	global_load_dwordx4 v[12:15], v[10:11], off
.LBB0_87:
	s_or_b64 exec, exec, s[16:17]
	v_mov_b32_e32 v9, 0
	v_mov_b32_e32 v10, 0
	v_mov_b32_e32 v11, 0
	s_and_saveexec_b64 s[16:17], s[18:19]
	v_add_u32_e32 v8, 48, v22
	v_ashrrev_i32_e32 v11, 31, v8
	v_mad_u64_u32 v[8:9], s[18:19], v8, s21, 0
	v_mov_b32_e32 v10, v9
	v_mad_u64_u32 v[10:11], s[18:19], v11, s21, v[10:11]
	v_mov_b32_e32 v9, v10
	v_lshl_add_u64 v[8:9], v[8:9], 2, v[20:21]
	global_load_dwordx4 v[8:11], v[8:9], off
.LBB0_89:
	s_or_b64 exec, exec, s[16:17]
	s_and_b64 vcc, exec, s[0:1]
	s_waitcnt lgkmcnt(0)
	s_barrier
	s_cbranch_vccnz .LBB0_53
	ds_read_b32 v20, v43
	ds_read_b32 v21, v44 offset:260
	s_cmp_lg_u64 s[6:7], 0
	s_cselect_b64 s[16:17], -1, 0
	s_cmp_eq_u64 s[6:7], 0
	s_cbranch_scc1 .LBB0_92
	s_waitcnt vmcnt(4) lgkmcnt(0)
	v_pk_mul_f32 v[20:21], v[20:21], v[60:61]
.LBB0_92:
	ds_read_b32 v22, v45
	ds_read_b32 v23, v44 offset:780
	v_cndmask_b32_e64 v24, 0, 1, s[16:17]
	v_cmp_ne_u32_e64 s[0:1], 1, v24
	s_andn2_b64 vcc, exec, s[16:17]
	s_cbranch_vccnz .LBB0_94
	s_ashr_i32 s9, s8, 31
	s_waitcnt lgkmcnt(0)
	v_pk_mul_f32 v[22:23], v[22:23], v[62:63]
.LBB0_94:
	ds_read_b32 v24, v46
	ds_read_b32 v25, v44 offset:1300
	s_and_b64 vcc, exec, s[0:1]
	s_cbranch_vccnz .LBB0_96
	s_ashr_i32 s9, s8, 31
	s_waitcnt lgkmcnt(0)
	v_pk_mul_f32 v[24:25], v[24:25], v[64:65]
.LBB0_96:
	ds_read_b32 v26, v47
	ds_read_b32 v27, v44 offset:1820
	s_and_b64 vcc, exec, s[0:1]
	s_cbranch_vccnz .LBB0_98
	s_ashr_i32 s9, s8, 31
	s_waitcnt lgkmcnt(0)
	v_pk_mul_f32 v[26:27], v[26:27], v[66:67]
.LBB0_98:
	ds_read_b32 v28, v48
	ds_read_b32 v29, v44 offset:2340
	s_and_b64 vcc, exec, s[0:1]
	s_cbranch_vccnz .LBB0_100
	s_ashr_i32 s9, s8, 31
	s_waitcnt lgkmcnt(0)
	v_pk_mul_f32 v[28:29], v[28:29], v[68:69]
.LBB0_100:
	ds_read_b32 v30, v49
	ds_read_b32 v31, v44 offset:2860
	s_and_b64 vcc, exec, s[0:1]
	s_cbranch_vccnz .LBB0_102
	s_ashr_i32 s9, s8, 31
	s_waitcnt lgkmcnt(0)
	v_pk_mul_f32 v[30:31], v[30:31], v[70:71]
.LBB0_102:
	ds_read_b32 v32, v50
	ds_read_b32 v33, v51 offset:260
	s_and_b64 vcc, exec, s[0:1]
	s_cbranch_vccnz .LBB0_104
	s_ashr_i32 s9, s8, 31
	s_waitcnt lgkmcnt(0)
	v_pk_mul_f32 v[32:33], v[32:33], v[72:73]
.LBB0_104:
	ds_read_b32 v34, v52
	ds_read_b32 v35, v51 offset:780
	s_and_b64 vcc, exec, s[16:17]
	s_cbranch_vccz .LBB0_106
	s_ashr_i32 s9, s8, 31
	s_waitcnt lgkmcnt(0)
	v_pk_mul_f32 v[36:37], v[34:35], v[74:75]
	s_cbranch_execnz .LBB0_52
	s_branch .LBB0_51
